# P2 diff and retention loops: scalar address arithmetic of the per-step LDS-DMA block moved into the m0-write hazard slots (6 s_nops per step pair removed)
# speedup vs baseline: 1.0187x; 1.0033x over previous
; template <bool DIFF>
; __device__ __forceinline__ void attn_item(LAS unsigned char* lds, const bf16_t* Z, bf16_t* MIX, int b, int h, int t, float lam, float shift, const float* gain, int tid, int wid, int lane) {
;     ...
;     lane = lane_id(); asm volatile("" : "+v"(lane)); tid = wid * 64 + lane;
;     const int q16 = lane & 15, quad = lane >> 4;
;     const int row0 = b * SEQ + 128 * t + 16 * wid;
;     const int cq = 2 * t + (wid >> 2), nkt = 2 * t + 2;
;     const int qcol = DIFF ? (3072 + 128 * h) : (64 * h);
;     const int kcol = DIFF ? (4096 + 128 * h) : (512 + 64 * h);
;     const int vcol = DIFF ? (5120 + 128 * h) : (1024 + 128 * h);
;     const int gcol = DIFF ? (6144 + 128 * h) : (2048 + 128 * h);
;     const float lg = lg2gamma(h);
;     bf16x8 qf[NC][2];
;     { const bf16_t* qrow = Z + (size_t)(row0 + q16) * DIN + qcol;
; #pragma unroll
;       for (int c = 0; c < NC; ++c)
; #pragma unroll
;           for (int ds = 0; ds < 2; ++ds) qf[c][ds] = __builtin_nontemporal_load((const bf16x8*)(qrow + 64 * c + 32 * ds + 8 * quad)); }
;     f32x4 O[NC][8]; float l[NC];
; #pragma unroll
;     for (int c = 0; c < NC; ++c) { l[c] = 0.f;
; #pragma unroll
;         for (int eb = 0; eb < 8; ++eb) O[c][eb] = (f32x4){0.f, 0.f, 0.f, 0.f}; }
;     const char* kbase = (const char*)(Z + (size_t)(b * SEQ) * DIN + kcol);
;     const char* vbase = (const char*)(Z + (size_t)(b * SEQ) * DIN + vcol);
;     const unsigned krow = (unsigned)(8 * wid + (lane >> 3));
;     const unsigned kso = (krow * DIN + 8u * ((unsigned)(lane & 7) ^ (krow & 7u))) * 2u;
;     const unsigned vrow = (unsigned)(4 * wid + (lane >> 4));
;     const unsigned vso = (vrow * DIN + 8u * (2u * ((((unsigned)lane & 15u) >> 1) ^ (vrow & 7u)) + ((unsigned)lane & 1u))) * 2u;
;     constexpr int ATT_RING = 32768;
;     ...
;     asm volatile("s_waitcnt lgkmcnt(0)\n\ts_barrier" ::: "memory");
;     ATT_DMA(0, 0); ATT_DMA(1, 1);
;     ATT_WAITBAR_ONE();
;     const unsigned kfo = (unsigned)(q16 * 128), ksw = (unsigned)(q16 & 7);
;     const unsigned vrr = (unsigned)(4 * quad + (q16 >> 2)), vx32 = (vrr & 7u) * 32u, vb0 = 16384u + vrr * 256u + 8u * (unsigned)(q16 & 3);
;     const float iq = (float)(128 * t + 16 * wid + q16);
;     int bcur = 0;
;     for (int kt = 0; kt < nkt; ++kt) {
;         const int bnx = (bcur == 2) ? 0 : bcur + 1, bn2 = (bnx == 2) ? 0 : bnx + 1;
;         const bool more2 = (kt + 2 < nkt);
.LBB0_565:
	v_writelane_b32 v254, s2, 51
	s_and_b32 s0, s2, 0xfffff800
	s_mul_hi_i32 s6, s0, 0x3800
	s_mul_i32 s7, s0, 0x3800
	v_readlane_b32 s0, v254, 25
	s_add_u32 s0, s0, s7
	v_readlane_b32 s1, v254, 26
	s_addc_u32 s1, s1, s6
	s_bfe_u32 s9, s95, 0x30003
	s_lshl_b32 s26, s9, 8
	s_add_u32 s76, s0, s26
	s_addc_u32 s77, s1, 0
	s_and_b32 s10, s95, 7
	s_lshl_b32 s0, s10, 2
	s_lshr_b32 s0, s99, s0
	s_and_b32 s0, s0, 15
	s_lshl_b32 s1, s95, 5
	s_and_b32 s11, s1, 0xfffff800
	s_lshl_b32 s8, s0, 7
	v_mov_b32_e32 v8, v183
	s_or_b32 s1, s8, s11
	s_add_i32 s45, s1, s29
	v_and_b32_e32 v9, 15, v8
	v_or_b32_e32 v124, s45, v9
	v_mov_b64_e32 v[4:5], s[30:31]
	v_ashrrev_i32_e32 v10, 4, v8
	s_lshl_b32 s70, s0, 1
	v_mad_i64_i32 v[4:5], s[0:1], v124, s36, v[4:5]
	s_add_i32 s83, s70, s66
	s_lshl_b32 s80, s9, 7
	v_lshl_add_u64 v[126:127], v[4:5], 0, s[26:27]
	v_lshlrev_b32_e32 v4, 3, v10
	s_mul_i32 s1, s11, 0x3800
	v_ashrrev_i32_e32 v5, 31, v4
	s_mul_hi_i32 s0, s11, 0x3800
	s_add_u32 s12, s30, s1
	v_lshl_add_u64 v[4:5], v[4:5], 1, v[126:127]
	s_addc_u32 s13, s31, s0
	v_lshl_add_u64 v[6:7], v[4:5], 0, s[14:15]
	v_add_co_u32_e32 v4, vcc, s16, v4
	s_add_u32 s71, s12, s26
	s_nop 0
	v_addc_co_u32_e32 v5, vcc, 0, v5, vcc
	global_load_dwordx4 v[76:79], v[6:7], off offset:64 nt
	global_load_dwordx4 v[72:75], v[6:7], off offset:128 nt
	global_load_dwordx4 v[80:83], v[4:5], off offset:2048 nt
	global_load_dwordx4 v[68:71], v[6:7], off offset:192 nt
	s_addc_u32 s94, s13, 0
	v_ashrrev_i32_e32 v4, 3, v8
	s_add_u32 s0, s71, 0x2000
	v_add_u32_e32 v5, s34, v4
	v_xor_b32_e32 v4, v4, v8
	s_addc_u32 s1, s94, 0
	v_mul_lo_u32 v5, v5, s37
	v_lshlrev_b32_e32 v4, 3, v4
	s_add_u32 s2, s71, 0x2800
	v_and_or_b32 v4, v4, 56, v5
	v_writelane_b32 v254, s0, 52
	s_addc_u32 s3, s94, 0
	v_lshlrev_b32_e32 v180, 1, v4
	v_add_u32_e32 v4, s35, v10
	v_writelane_b32 v254, s1, 53
	v_lshlrev_b32_e32 v5, 1, v4
	v_writelane_b32 v254, s2, 54
	v_xor_b32_e32 v5, v5, v8
	v_and_b32_e32 v6, 1, v8
	s_waitcnt lgkmcnt(0)
	s_barrier
	v_writelane_b32 v254, s3, 55
	s_add_u32 s4, s2, 0x70000
	s_mov_b32 m0, s90
	v_and_or_b32 v6, v5, 14, v6
	v_mul_lo_u32 v7, v4, s36
	s_addc_u32 s5, s3, 0
	v_lshl_add_u64 v[4:5], s[0:1], 0, v[180:181]
	global_load_lds_dwordx4 v180, s[0:1]
	v_lshl_add_u64 v[4:5], v[4:5], 0, s[96:97]
	s_mov_b32 m0, s17
	v_lshl_or_b32 v132, v6, 4, v7
	global_load_lds_dwordx4 v[4:5], off
	s_mov_b32 m0, s43
	s_add_u32 s0, s71, 0xe2000
	global_load_lds_dwordx4 v132, s[2:3]
	s_mov_b32 m0, s38
	s_addc_u32 s1, s94, 0
	global_load_lds_dwordx4 v132, s[4:5]
	v_writelane_b32 v254, s0, 56
	s_add_u32 s4, s71, 0xe2800
	s_addc_u32 s5, s94, 0
	v_writelane_b32 v254, s1, 57
	v_writelane_b32 v254, s4, 58
	s_mov_b32 m0, s39
	v_lshl_add_u64 v[4:5], s[0:1], 0, v[180:181]
	v_writelane_b32 v254, s5, 59
	s_add_u32 s14, s4, 0x70000
	s_addc_u32 s15, s5, 0
	global_load_lds_dwordx4 v180, s[0:1]
	v_lshl_add_u64 v[4:5], v[4:5], 0, s[96:97]
	s_mov_b32 m0, s18
	v_lshlrev_b32_e32 v128, 2, v10
	global_load_lds_dwordx4 v[4:5], off
	s_mov_b32 m0, s40
	v_bfe_u32 v4, v8, 2, 2
	global_load_lds_dwordx4 v132, s[4:5]
	s_mov_b32 m0, s41
	v_lshlrev_b32_e32 v6, 3, v8
	global_load_lds_dwordx4 v132, s[14:15]
	v_or_b32_e32 v4, v128, v4
	v_and_b32_e32 v6, 24, v6
	v_lshlrev_b32_e32 v5, 5, v4
	v_lshl_or_b32 v4, v4, 8, v6
	v_add_u32_e32 v143, 0x4000, v4
	v_bitop3_b32 v4, v10, v8, 7 bitop3:0x78
	v_lshlrev_b32_e32 v145, 4, v4
	v_add_u32_e32 v4, 4, v10
	v_bitop3_b32 v4, v4, v8, 7 bitop3:0x78
	v_mov_b32_e32 v6, v181
	v_mov_b32_e32 v7, v181
	v_lshlrev_b32_e32 v144, 7, v9
	v_and_b32_e32 v142, 0xe0, v5
	v_lshlrev_b32_e32 v146, 4, v4
	v_bitop3_b32 v141, v5, 32, v186 bitop3:0x6c
	v_bitop3_b32 v140, v5, 64, v186 bitop3:0x6c
	v_bitop3_b32 v139, v5, s73, v186 bitop3:0x6c
	v_bitop3_b32 v138, v5, s74, v186 bitop3:0x6c
	v_bitop3_b32 v137, v5, s75, v186 bitop3:0x6c
	v_bitop3_b32 v136, v5, s79, v186 bitop3:0x6c
	v_bitop3_b32 v129, v5, s67, v5 bitop3:0xc
	v_mov_b32_e32 v4, v181
	v_mov_b32_e32 v5, v181
	v_mov_b64_e32 v[14:15], v[6:7]
	v_mov_b64_e32 v[22:23], v[6:7]
	v_mov_b64_e32 v[30:31], v[6:7]
	v_mov_b64_e32 v[38:39], v[6:7]
	v_mov_b64_e32 v[46:47], v[6:7]
	v_mov_b64_e32 v[54:55], v[6:7]
	v_mov_b64_e32 v[58:59], v[6:7]
	v_mov_b64_e32 v[10:11], v[6:7]
	v_mov_b64_e32 v[18:19], v[6:7]
	v_mov_b64_e32 v[26:27], v[6:7]
	v_mov_b64_e32 v[34:35], v[6:7]
	v_mov_b64_e32 v[42:43], v[6:7]
	v_mov_b64_e32 v[50:51], v[6:7]
	v_mov_b64_e32 v[62:63], v[6:7]
	v_mov_b64_e32 v[66:67], v[6:7]
	v_ashrrev_i32_e32 v125, 31, v124
	s_mov_b32 s17, 0
	v_mov_b32_e32 v133, v181
	v_mov_b32_e32 v130, v181
	v_mov_b32_e32 v131, v181
	s_mov_b64 s[4:5], s[76:77]
	v_mov_b64_e32 v[12:13], v[4:5]
	v_mov_b64_e32 v[20:21], v[4:5]
	v_mov_b64_e32 v[28:29], v[4:5]
	v_mov_b64_e32 v[36:37], v[4:5]
	v_mov_b64_e32 v[44:45], v[4:5]
	v_mov_b64_e32 v[52:53], v[4:5]
	v_mov_b64_e32 v[56:57], v[4:5]
	v_mov_b64_e32 v[8:9], v[4:5]
	v_mov_b64_e32 v[16:17], v[4:5]
	v_mov_b64_e32 v[24:25], v[4:5]
	v_mov_b64_e32 v[32:33], v[4:5]
	v_mov_b64_e32 v[40:41], v[4:5]
	v_mov_b64_e32 v[48:49], v[4:5]
	v_mov_b64_e32 v[60:61], v[4:5]
	s_mov_b32 s15, 0
	v_mov_b64_e32 v[64:65], v[4:5]
	s_waitcnt vmcnt(4) lgkmcnt(0)
	s_barrier
	s_mov_b64 s[4:5], s[76:77]
	s_mov_b32 s15, 0
	s_and_b32 s0, s15, 3
	s_lshl_b32 s0, s0, 15
	s_add_i32 s1, s15, 3
	s_and_b32 s1, s1, 3
	s_lshl_b32 s1, s1, 15
	s_add_i32 s16, s15, 2
	s_and_b32 s16, s16, 3
	s_lshl_b32 s16, s16, 15
	s_add_i32 s16, s16, s90
	v_add_u32_e32 v119, s0, v144
	v_add_u32_e32 v116, v119, v145
	v_add_u32_e32 v117, v119, v146
	ds_read_b128 v[84:87], v116
	ds_read_b128 v[88:91], v116 offset:2048
	ds_read_b128 v[92:95], v117
	ds_read_b128 v[96:99], v117 offset:2048
	ds_read_b128 v[100:103], v116 offset:4096
	ds_read_b128 v[104:107], v116 offset:6144
	ds_read_b128 v[108:111], v117 offset:4096
	ds_read_b128 v[112:115], v117 offset:6144
	s_cmp_ge_u32 s15, s70
	s_cbranch_scc1 .Ldx_nd0
	s_add_u32 s18, s4, 0xfffff800
	s_addc_u32 s19, s5, -1
	s_mov_b32 m0, s16
	s_add_u32 s22, s18, 0x80
	s_addc_u32 s23, s19, 0
	global_load_lds_dwordx4 v180, s[18:19]
	s_add_i32 m0, s16, 0x2000
	s_add_u32 s24, s4, 0x70000
	s_addc_u32 s25, s5, 0
	global_load_lds_dwordx4 v180, s[22:23]
	s_add_i32 m0, s16, 0x4000
	s_nop 0
	global_load_lds_dwordx4 v132, s[4:5]
	s_add_i32 m0, s16, 0x6000
	s_add_u32 s4, s4, 0xe0000
	s_addc_u32 s5, s5, 0
	global_load_lds_dwordx4 v132, s[24:25]

; #define LAS __attribute__((address_space(3)))
; #define ATT_KREAD(dst, c) do { _Pragma("unroll") for (int kb = 0; kb < 4; ++kb) _Pragma("unroll") for (int ds = 0; ds < 2; ++ds) \
;                 dst[kb * 2 + ds] = *(const LAS bf16x8*)(bp + (c) * 8192 + kb * 2048 + kfo + (((unsigned)(4 * ds + quad) ^ ksw) * 16)); } while (0)
; #define ATT_SMMA(sv, kf, c) do { _Pragma("unroll") for (int kb = 0; kb < 4; ++kb) { sv[kb] = (f32x4){sinit, sinit, sinit, sinit}; _Pragma("unroll") for (int ds = 0; ds < 2; ++ds) \
;                 sv[kb] = __builtin_amdgcn_mfma_f32_16x16x32_bf16(kf[kb * 2 + ds], qf[c][ds], sv[kb], 0, 0, 0); } } while (0)
; #define ATT_PV(c, lo_, hi_, eb0) do { _Pragma("unroll") for (int e = 0; e < 4; ++e) _Pragma("unroll") for (int ks = 0; ks < 2; ++ks) \
;                 O[c][(eb0) + e] = __builtin_amdgcn_mfma_f32_16x16x32_bf16(__builtin_shufflevector(lo_[e * 2 + ks], hi_[e * 2 + ks], 0, 1, 2, 3, 4, 5, 6, 7), P[c][ks], O[c][(eb0) + e], 0, 0, 0); } while (0)
; #define ATT_SB __builtin_amdgcn_sched_barrier(0)
; template <bool DIFF>
; __device__ __forceinline__ void attn_item(LAS unsigned char* lds, const bf16_t* Z, bf16_t* MIX, int b, int h, int t, float lam, float shift, const float* gain, int tid, int wid, int lane) {
;     ...
;     for (int kt = 0; kt < nkt; ++kt) {
;         const int bnx = (bcur == 2) ? 0 : bcur + 1, bn2 = (bnx == 2) ? 0 : bnx + 1;
;         const bool more2 = (kt + 2 < nkt);
;         if (more2) ATT_DMA(kt + 2, bn2);
;         if (kt <= cq) {
;             LAS unsigned char* bp = lds + bcur * ATT_RING;
;             const float msk = 0.f;
;             const float sinit = DIFF ? (msk - shift) : 0.f;
;             bf16x8 kfA[8], kfB[8]; s16x4 vAl[8], vAh[8], vBl[8], vBh[8];
;             f32x4 s0[4], s1[4];
;             bf16x8 P[NC][2];
;             const unsigned bpa = (unsigned)(size_t)bp;
;     ...
;             ATT_KREAD(kfA, 0); ATT_SB;
;             if (DIFF) { ATT_KREAD(kfB, NC - 1); ATT_SMMA(s0, kfA, 0); ATT_SB;
;                         ATT_VISSUE(vAl, vAh, 0); ATT_SMMA(s1, kfB, NC - 1); ATT_SOFT(s0, 0); ATT_SB;
;                         ATT_SOFT(s1, NC - 1); ATT_PVW(0, vAl, vAh, 0); ATT_SB;
;                         ATT_VISSUE(vBl, vBh, 4); ATT_PV(NC - 1, vAl, vAh, 0); ATT_SB;
;                         ATT_PVW(0, vBl, vBh, 4); ATT_PV(NC - 1, vBl, vBh, 4); ATT_SB; }
.Ldx_loop:
	s_and_b32 s0, s15, 3
	s_lshl_b32 s0, s0, 15
	s_add_i32 s1, s15, 3
	s_and_b32 s1, s1, 3
	s_lshl_b32 s1, s1, 15
	s_add_i32 s16, s15, 2
	s_and_b32 s16, s16, 3
	s_lshl_b32 s16, s16, 15
	s_add_i32 s16, s16, s90
	s_cmp_gt_u32 s15, s83
	s_cbranch_scc1 .Ldx_pvo
	s_waitcnt lgkmcnt(0)
	v_add_u32_e32 v119, s0, v144
	v_add_u32_e32 v116, v119, v145
	v_add_u32_e32 v117, v119, v146
	ds_read_b128 v[84:87], v116
	ds_read_b128 v[88:91], v116 offset:2048
	ds_read_b128 v[92:95], v117
	ds_read_b128 v[96:99], v117 offset:2048
	ds_read_b128 v[100:103], v116 offset:4096
	ds_read_b128 v[104:107], v116 offset:6144
	ds_read_b128 v[108:111], v117 offset:4096
	ds_read_b128 v[112:115], v117 offset:6144
	v_add_u32_e32 v118, s1, v143
	v_add_u32_e32 v120, v118, v138
	v_add_u32_e32 v121, v118, v137
	v_add_u32_e32 v122, v118, v136
	v_add_u32_e32 v123, v118, v129
	v_mfma_f32_16x16x32_bf16 v[64:67], v[148:151], v[220:223], v[64:67]
	v_add_f32_e32 v131, v131, v188
	v_add_f32_e32 v131, v131, v189
	v_mfma_f32_16x16x32_bf16 v[60:63], v[156:159], v[220:223], v[60:63]
	v_add_f32_e32 v131, v131, v190
	v_add_f32_e32 v131, v131, v191
	v_mfma_f32_16x16x32_bf16 v[56:59], v[148:151], v[228:231], v[56:59]
	v_add_f32_e32 v131, v131, v192
	v_add_f32_e32 v131, v131, v193
	v_mfma_f32_16x16x32_bf16 v[52:55], v[156:159], v[228:231], v[52:55]
	v_add_f32_e32 v131, v131, v194
	v_add_f32_e32 v131, v131, v195
	v_mfma_f32_16x16x32_bf16 v[64:67], v[152:155], v[224:227], v[64:67]
	v_add_f32_e32 v131, v131, v196
	v_add_f32_e32 v131, v131, v197
	v_mfma_f32_16x16x32_bf16 v[60:63], v[160:163], v[224:227], v[60:63]
	v_add_f32_e32 v131, v131, v198
	v_add_f32_e32 v131, v131, v199
	v_mfma_f32_16x16x32_bf16 v[56:59], v[152:155], v[232:235], v[56:59]
	v_add_f32_e32 v131, v131, v200
	v_add_f32_e32 v131, v131, v201
	v_mfma_f32_16x16x32_bf16 v[52:55], v[160:163], v[232:235], v[52:55]
	v_add_f32_e32 v131, v131, v202
	v_add_f32_e32 v131, v131, v203
	ds_read_b64_tr_b16 v[148:149], v120
	ds_read_b64_tr_b16 v[150:151], v120 offset:4096
	ds_read_b64_tr_b16 v[152:153], v120 offset:8192
	ds_read_b64_tr_b16 v[154:155], v120 offset:12288
	ds_read_b64_tr_b16 v[156:157], v121
	ds_read_b64_tr_b16 v[158:159], v121 offset:4096
	ds_read_b64_tr_b16 v[160:161], v121 offset:8192
	ds_read_b64_tr_b16 v[162:163], v121 offset:12288
	v_mfma_f32_16x16x32_bf16 v[48:51], v[164:167], v[220:223], v[48:51]
	v_add_f32_e32 v130, v130, v204
	v_add_f32_e32 v130, v130, v205
	v_mfma_f32_16x16x32_bf16 v[40:43], v[172:175], v[220:223], v[40:43]
	v_add_f32_e32 v130, v130, v206
	v_add_f32_e32 v130, v130, v207
	v_mfma_f32_16x16x32_bf16 v[44:47], v[164:167], v[228:231], v[44:47]
	v_add_f32_e32 v130, v130, v208
	v_add_f32_e32 v130, v130, v209
	v_mfma_f32_16x16x32_bf16 v[36:39], v[172:175], v[228:231], v[36:39]
	v_add_f32_e32 v130, v130, v210
	v_add_f32_e32 v130, v130, v211
	v_mfma_f32_16x16x32_bf16 v[48:51], v[168:171], v[224:227], v[48:51]
	v_add_f32_e32 v130, v130, v212
	v_add_f32_e32 v130, v130, v213
	v_mfma_f32_16x16x32_bf16 v[40:43], v[176:179], v[224:227], v[40:43]
	v_add_f32_e32 v130, v130, v214
	v_add_f32_e32 v130, v130, v215
	v_mfma_f32_16x16x32_bf16 v[44:47], v[168:171], v[232:235], v[44:47]
	v_add_f32_e32 v130, v130, v216
	v_add_f32_e32 v130, v130, v217
	v_mfma_f32_16x16x32_bf16 v[36:39], v[176:179], v[232:235], v[36:39]
	v_add_f32_e32 v130, v130, v218
	v_add_f32_e32 v130, v130, v219
	ds_read_b64_tr_b16 v[164:165], v122
	ds_read_b64_tr_b16 v[166:167], v122 offset:4096
	ds_read_b64_tr_b16 v[168:169], v122 offset:8192
	ds_read_b64_tr_b16 v[170:171], v122 offset:12288
	ds_read_b64_tr_b16 v[172:173], v123
	ds_read_b64_tr_b16 v[174:175], v123 offset:4096
	ds_read_b64_tr_b16 v[176:177], v123 offset:8192
	ds_read_b64_tr_b16 v[178:179], v123 offset:12288
	s_cmp_ge_u32 s15, s70
	s_cbranch_scc1 .Ldx_nd
	s_add_u32 s18, s4, 0xfffff800
	s_addc_u32 s19, s5, -1
	s_mov_b32 m0, s16
	s_add_u32 s22, s18, 0x80
	s_addc_u32 s23, s19, 0
	global_load_lds_dwordx4 v180, s[18:19]
	s_add_i32 m0, s16, 0x2000
	s_add_u32 s24, s4, 0x70000
	s_addc_u32 s25, s5, 0
	global_load_lds_dwordx4 v180, s[22:23]
	s_add_i32 m0, s16, 0x4000
	s_nop 0
	global_load_lds_dwordx4 v132, s[4:5]
	s_add_i32 m0, s16, 0x6000
	s_add_u32 s4, s4, 0xe0000
	s_addc_u32 s5, s5, 0
	global_load_lds_dwordx4 v132, s[24:25]

; __device__ __forceinline__ int lane_id() { return (int)__builtin_amdgcn_mbcnt_hi(~0u, __builtin_amdgcn_mbcnt_lo(~0u, 0u)); }
; __device__ __forceinline__ void ret_pair(LAS unsigned char* lds, const bf16_t* Z, bf16_t* MIX, int b, int h, int tA, int tB, const float* gain, int wid) {
;     int lane = lane_id(); asm volatile("" : "+v"(lane));
;     const int q16 = lane & 15, quad = lane >> 4;
;     const int rowA0 = b * SEQ + 128 * tA + 16 * wid, rowB0 = b * SEQ + 128 * tB + 16 * wid;
;     const int cqA = 2 * tA + (wid >> 2), cqB = 2 * tB + (wid >> 2), nkt = 2 * tA + 2;
;     const int qcol = 64 * h, kcol = 512 + 64 * h, vcol = 1024 + 128 * h, gcol = 2048 + 128 * h;
;     const float lg = lg2gamma(h);
;     bf16x8 qfA[2], qfB[2];
;     { const bf16_t* qa = Z + (size_t)(rowA0 + q16) * DIN + qcol; const bf16_t* qb = Z + (size_t)(rowB0 + q16) * DIN + qcol;
; #pragma unroll
;       for (int ds = 0; ds < 2; ++ds) { qfA[ds] = __builtin_nontemporal_load((const bf16x8*)(qa + 32 * ds + 8 * quad)); qfB[ds] = __builtin_nontemporal_load((const bf16x8*)(qb + 32 * ds + 8 * quad)); } }
;     f32x4 OA[8], OB[8];
; #pragma unroll
;     for (int eb = 0; eb < 8; ++eb) { OA[eb] = (f32x4){0.f, 0.f, 0.f, 0.f}; OB[eb] = OA[eb]; }
;     const char* kbase = (const char*)(Z + (size_t)(b * SEQ) * DIN + kcol);
;     const char* vbase = (const char*)(Z + (size_t)(b * SEQ) * DIN + vcol);
;     const unsigned krow = (unsigned)(8 * wid + (lane >> 3));
;     const unsigned kso = (krow * DIN + 8u * ((unsigned)(lane & 7) ^ (krow & 7u))) * 2u;
;     const unsigned vrow = (unsigned)(4 * wid + (lane >> 4));
;     const unsigned vso = (vrow * DIN + 8u * (2u * ((((unsigned)lane & 15u) >> 1) ^ (vrow & 7u)) + ((unsigned)lane & 1u))) * 2u;
;     constexpr int RING = 32768;
;     ...
;     asm volatile("s_waitcnt lgkmcnt(0)\n\ts_barrier" ::: "memory");
;     RP_DMA(0, 0); RP_DMA(1, 1);
;     asm volatile("s_waitcnt vmcnt(3) lgkmcnt(0)\n\ts_barrier" ::: "memory");
;     const unsigned kfo = (unsigned)(q16 * 128), ksw = (unsigned)(q16 & 7);
;     const unsigned vrr = (unsigned)(4 * quad + (q16 >> 2)), vx32 = (vrr & 7u) * 32u, vb0 = 16384u + vrr * 256u + 8u * (unsigned)(q16 & 3);
;     const float iqA = (float)(128 * tA + 16 * wid + q16), iqB = (float)(128 * tB + 16 * wid + q16);
.LBB0_595:
	s_lshl_b32 s1, s10, 2
	s_lshr_b32 s1, 0x76543210, s1
	s_and_b32 s1, s1, 15
	s_lshl_b32 s14, s1, 8
	s_or_b32 s0, s14, s11
	v_writelane_b32 v255, s95, 1
	s_add_i32 s5, s0, s29
	s_add_i32 s8, s14, 0x80
	s_or_b32 s45, s8, s11
	s_add_i32 s45, s45, s29
	s_lshl_b32 s82, s1, 2
	s_add_i32 s70, s82, 2
	s_add_i32 s83, s70, s66
	s_add_i32 s0, s70, -1
	s_cmp_lt_u32 s0, s83
	s_cselect_b64 s[2:3], -1, 0
	v_writelane_b32 v254, s2, 60
	v_writelane_b32 v254, s3, 61
	v_writelane_b32 v254, s0, 62
	s_cmp_lt_u32 s70, s83
	s_cselect_b64 s[2:3], -1, 0
	v_writelane_b32 v254, s2, 63
	v_writelane_b32 v255, s3, 0
	v_writelane_b32 v255, s44, 2
	s_mov_b32 s0, s82
	s_add_i32 s91, s82, s66
	v_writelane_b32 v255, s0, 3
	s_add_i32 s72, s66, s0
	v_readlane_b32 s0, v254, 28
	s_add_u32 s0, s0, s7
	v_readlane_b32 s1, v254, 29
	s_addc_u32 s1, s1, s6
	s_add_u32 s2, s0, s26
	s_addc_u32 s3, s1, 0
	v_readlane_b32 s0, v254, 30
	s_add_u32 s0, s0, s7
	v_readlane_b32 s1, v254, 31
	v_and_b32_e32 v14, 15, v15
	s_addc_u32 s1, s1, s6
	s_lshl_b32 s4, s9, 7
	s_add_u32 s84, s0, s4
	v_or_b32_e32 v6, s45, v14
	v_mov_b64_e32 v[4:5], s[30:31]
	s_addc_u32 s85, s1, 0
	v_mad_i64_i32 v[6:7], s[0:1], v6, s36, v[4:5]
	v_writelane_b32 v255, s45, 4
	s_mov_b32 s1, s27
	v_writelane_b32 v255, s0, 5
	v_or_b32_e32 v8, s5, v14
	s_mov_b32 s81, s27
	v_writelane_b32 v255, s1, 6
	v_mad_i64_i32 v[4:5], s[0:1], v8, s36, v[4:5]
	s_add_u32 s9, s12, s80
	v_ashrrev_i32_e32 v13, 3, v15
	v_ashrrev_i32_e32 v17, 4, v15
	v_lshl_add_u64 v[6:7], v[6:7], 0, s[80:81]
	v_lshl_add_u64 v[4:5], v[4:5], 0, s[80:81]
	s_addc_u32 s81, s13, 0
	v_add_u32_e32 v16, s34, v13
	v_xor_b32_e32 v13, v13, v15
	v_lshlrev_b32_e32 v8, 3, v17
	s_add_u32 s4, s9, 0x400
	v_mul_lo_u32 v16, v16, s37
	v_lshlrev_b32_e32 v13, 3, v13
	v_writelane_b32 v255, s5, 7
	v_ashrrev_i32_e32 v9, 31, v8
	s_addc_u32 s5, s81, 0
	v_and_or_b32 v13, v13, 56, v16
	v_lshlrev_b64 v[8:9], 1, v[8:9]
	s_add_u32 s0, s71, 0x800
	v_lshlrev_b32_e32 v180, 1, v13
	v_add_u32_e32 v13, s35, v17
	v_lshl_add_u64 v[6:7], v[6:7], 0, v[8:9]
	v_lshl_add_u64 v[4:5], v[4:5], 0, v[8:9]
	s_addc_u32 s1, s94, 0
	v_lshlrev_b32_e32 v16, 1, v13
	global_load_dwordx4 v[32:35], v[6:7], off nt
	global_load_dwordx4 v[8:11], v[4:5], off nt
	global_load_dwordx4 v[28:31], v[6:7], off offset:64 nt
	s_nop 0
	global_load_dwordx4 v[4:7], v[4:5], off offset:64 nt
	v_xor_b32_e32 v16, v16, v15
	v_and_b32_e32 v18, 1, v15
	s_waitcnt lgkmcnt(0)
	s_barrier
	s_add_u32 s6, s0, 0x70000
	v_and_or_b32 v16, v16, 14, v18
	v_mul_lo_u32 v13, v13, s36
	s_addc_u32 s7, s1, 0
	s_mov_b32 m0, s90
	v_lshl_or_b32 v184, v16, 4, v13
	global_load_lds_dwordx4 v180, s[4:5]
	s_mov_b32 m0, s43
	v_lshlrev_b32_e32 v16, 2, v17
	global_load_lds_dwordx4 v184, s[0:1]
	s_add_u32 s0, s9, 0xe0400
	s_addc_u32 s1, s81, 0
	s_add_u32 s4, s71, 0xe0800
	v_bfe_u32 v13, v15, 2, 2
	v_lshlrev_b32_e32 v19, 3, v15
	s_mov_b32 m0, s38
	s_addc_u32 s5, s94, 0
	v_or_b32_e32 v18, v16, v13
	v_and_b32_e32 v19, 24, v19
	global_load_lds_dwordx4 v184, s[6:7]
	s_add_u32 s6, s4, 0x70000
	v_lshlrev_b32_e32 v13, 5, v18
	v_lshl_or_b32 v18, v18, 8, v19
	v_bitop3_b32 v19, v17, v15, 7 bitop3:0x78
	v_add_u32_e32 v17, 4, v17
	s_addc_u32 s7, s5, 0
	s_add_i32 s8, s8, s29
	v_bitop3_b32 v15, v17, v15, 7 bitop3:0x78
	v_add_u32_e32 v188, 0x4000, v18
	v_or_b32_e32 v18, s8, v14
	v_lshlrev_b32_e32 v205, 4, v15
	v_lshl_add_u32 v15, s83, 6, v16
	v_cvt_f32_u32_e32 v18, v18
	v_cvt_f32_i32_e32 v17, v15
	s_mov_b32 m0, s39
	v_writelane_b32 v255, s9, 8
	v_sub_f32_e32 v17, v17, v18
	global_load_lds_dwordx4 v180, s[0:1]
	v_cmp_lt_f32_e64 s[0:1], 0, v17
	v_mul_f32_e32 v17, v17, v12
	v_exp_f32_e32 v189, v17
	v_or_b32_e32 v17, 1, v15
	v_cvt_f32_i32_e32 v17, v17
	s_mov_b32 m0, s40
	s_add_i32 s14, s14, s29
	global_load_lds_dwordx4 v184, s[4:5]
	v_sub_f32_e32 v17, v17, v18
	v_cmp_lt_f32_e64 s[68:69], 0, v17
	v_mul_f32_e32 v17, v17, v12
	v_exp_f32_e32 v190, v17
	v_or_b32_e32 v17, 2, v15
	v_cvt_f32_i32_e32 v17, v17
	s_mov_b32 m0, s41
	v_lshlrev_b32_e32 v201, 7, v14
	global_load_lds_dwordx4 v184, s[6:7]
	v_sub_f32_e32 v17, v17, v18
	v_cmp_lt_f32_e64 s[4:5], 0, v17
	v_mul_f32_e32 v17, v17, v12
	v_exp_f32_e32 v191, v17
	v_or_b32_e32 v17, 3, v15
	v_cvt_f32_i32_e32 v17, v17
	v_or_b32_e32 v14, s14, v14
	v_cvt_f32_u32_e32 v14, v14
	v_sub_f32_e32 v17, v17, v18
	v_cmp_lt_f32_e64 s[6:7], 0, v17
	v_mul_f32_e32 v17, v17, v12
	v_exp_f32_e32 v192, v17
	v_add_u32_e32 v17, 16, v15
	v_cvt_f32_i32_e32 v17, v17
	v_mov_b32_e32 v48, v181
	v_mov_b32_e32 v49, v181
	v_mov_b32_e32 v50, v181
	v_sub_f32_e32 v17, v17, v18
	v_cmp_lt_f32_e64 s[8:9], 0, v17
	v_mul_f32_e32 v17, v17, v12
	v_exp_f32_e32 v193, v17
	v_add_u32_e32 v17, 17, v15
	v_cvt_f32_i32_e32 v17, v17
	v_mov_b32_e32 v51, v181
	v_and_b32_e32 v187, 0xe0, v13
	v_lshlrev_b32_e32 v204, 4, v19
	v_sub_f32_e32 v17, v17, v18
	v_cmp_lt_f32_e64 s[10:11], 0, v17
	v_mul_f32_e32 v17, v17, v12
	v_exp_f32_e32 v194, v17
	v_add_u32_e32 v17, 18, v15
	v_cvt_f32_i32_e32 v17, v17
	v_bitop3_b32 v207, v13, 32, v186 bitop3:0x6c
	v_bitop3_b32 v226, v13, 64, v186 bitop3:0x6c
	v_bitop3_b32 v224, v13, s73, v186 bitop3:0x6c
	v_sub_f32_e32 v17, v17, v18
	v_cmp_lt_f32_e64 s[12:13], 0, v17
	v_mul_f32_e32 v17, v17, v12
	v_exp_f32_e32 v195, v17
	v_add_u32_e32 v17, 19, v15
	v_cvt_f32_i32_e32 v17, v17
	v_bitop3_b32 v221, v13, s74, v186 bitop3:0x6c
	v_bitop3_b32 v220, v13, s75, v186 bitop3:0x6c
	v_bitop3_b32 v217, v13, s79, v186 bitop3:0x6c
	v_sub_f32_e32 v17, v17, v18
	v_cmp_lt_f32_e64 s[14:15], 0, v17
	v_mul_f32_e32 v17, v17, v12
	v_exp_f32_e32 v196, v17
	v_add_u32_e32 v17, 32, v15
	v_cvt_f32_i32_e32 v17, v17
	v_bitop3_b32 v216, v13, s67, v13 bitop3:0xc
	v_mov_b64_e32 v[44:45], v[48:49]
; __device__ __forceinline__ void ret_pair(LAS unsigned char* lds, const bf16_t* Z, bf16_t* MIX, int b, int h, int tA, int tB, const float* gain, int wid) {
;     ...
;     const unsigned kfo = (unsigned)(q16 * 128), ksw = (unsigned)(q16 & 7);
;     const unsigned vrr = (unsigned)(4 * quad + (q16 >> 2)), vx32 = (vrr & 7u) * 32u, vb0 = 16384u + vrr * 256u + 8u * (unsigned)(q16 & 3);
;     const float iqA = (float)(128 * tA + 16 * wid + q16), iqB = (float)(128 * tB + 16 * wid + q16);
;     ...
;     int bcur = 0;
;     for (int kt = 0; kt < nkt; ++kt) {
;         const int bnx = (bcur == 2) ? 0 : bcur + 1, bn2 = (bnx == 2) ? 0 : bnx + 1;
;         const bool more2 = (kt + 2 < nkt);
;         if (more2) RP_DMA(kt + 2, bn2);
	v_mov_b64_e32 v[40:41], v[48:49]
	v_sub_f32_e32 v17, v17, v18
	v_cmp_lt_f32_e64 s[16:17], 0, v17
	v_mul_f32_e32 v17, v17, v12
	v_exp_f32_e32 v197, v17
	v_add_u32_e32 v17, 33, v15
	v_cvt_f32_i32_e32 v17, v17
	v_mov_b64_e32 v[36:37], v[48:49]
	v_mov_b64_e32 v[24:25], v[48:49]
	v_mov_b64_e32 v[20:21], v[48:49]
	v_sub_f32_e32 v17, v17, v18
	v_cmp_lt_f32_e64 s[18:19], 0, v17
	v_mul_f32_e32 v17, v17, v12
	v_exp_f32_e32 v198, v17
	v_add_u32_e32 v17, 34, v15
	v_cvt_f32_i32_e32 v17, v17
	v_mov_b64_e32 v[82:83], v[50:51]
	v_mov_b64_e32 v[78:79], v[50:51]
	v_mov_b64_e32 v[74:75], v[50:51]
	v_sub_f32_e32 v17, v17, v18
	v_cmp_lt_f32_e64 s[20:21], 0, v17
	v_mul_f32_e32 v17, v17, v12
	v_exp_f32_e32 v199, v17
	v_add_u32_e32 v17, 35, v15
	v_cvt_f32_i32_e32 v17, v17
	v_mov_b64_e32 v[70:71], v[50:51]
	v_mov_b64_e32 v[66:67], v[50:51]
	v_mov_b64_e32 v[62:63], v[50:51]
	v_sub_f32_e32 v17, v17, v18
	v_cmp_lt_f32_e64 s[22:23], 0, v17
	v_mul_f32_e32 v17, v17, v12
	v_exp_f32_e32 v200, v17
	v_add_u32_e32 v17, 48, v15
	v_cvt_f32_i32_e32 v17, v17
	v_mov_b64_e32 v[58:59], v[50:51]
	v_mov_b64_e32 v[54:55], v[50:51]
	v_mov_b32_e32 v185, v181
	v_sub_f32_e32 v17, v17, v18
	v_cmp_lt_f32_e64 s[24:25], 0, v17
	v_mul_f32_e32 v17, v17, v12
	v_exp_f32_e32 v203, v17
	v_add_u32_e32 v17, 49, v15
	v_cvt_f32_i32_e32 v17, v17
	s_mov_b32 s66, 0
	v_mov_b64_e32 v[46:47], v[50:51]
	v_mov_b64_e32 v[42:43], v[50:51]
	v_sub_f32_e32 v17, v17, v18
	v_cmp_lt_f32_e64 s[26:27], 0, v17
	v_mul_f32_e32 v17, v17, v12
	v_exp_f32_e32 v206, v17
	v_add_u32_e32 v17, 50, v15
	v_add_u32_e32 v15, 51, v15
	v_cvt_f32_i32_e32 v15, v15
	v_cvt_f32_i32_e32 v17, v17
	v_mov_b64_e32 v[38:39], v[50:51]
	v_mov_b64_e32 v[26:27], v[50:51]
	v_sub_f32_e32 v15, v15, v18
	v_cmp_lt_f32_e64 s[34:35], 0, v15
	v_mul_f32_e32 v15, v15, v12
	v_exp_f32_e32 v211, v15
	v_lshl_add_u32 v15, s91, 6, v16
	v_cvt_f32_i32_e32 v16, v15
	v_sub_f32_e32 v17, v17, v18
	v_cmp_lt_f32_e64 s[28:29], 0, v17
	v_mul_f32_e32 v17, v17, v12
	v_sub_f32_e32 v16, v16, v14
	v_cmp_lt_f32_e64 s[30:31], 0, v16
	v_mul_f32_e32 v16, v16, v12
	v_exp_f32_e32 v208, v16
	v_or_b32_e32 v16, 1, v15
	v_cvt_f32_i32_e32 v16, v16
	v_exp_f32_e32 v209, v17
	v_mov_b64_e32 v[22:23], v[50:51]
	v_mov_b64_e32 v[80:81], v[48:49]
	v_sub_f32_e32 v16, v16, v14
	v_cmp_lt_f32_e64 s[36:37], 0, v16
	v_mul_f32_e32 v16, v16, v12
	v_exp_f32_e32 v210, v16
	v_or_b32_e32 v16, 2, v15
	v_cvt_f32_i32_e32 v16, v16
	v_mov_b64_e32 v[76:77], v[48:49]
	v_mov_b64_e32 v[72:73], v[48:49]
	v_mov_b64_e32 v[68:69], v[48:49]
	v_sub_f32_e32 v16, v16, v14
	v_cmp_lt_f32_e64 s[38:39], 0, v16
	v_mul_f32_e32 v16, v16, v12
	v_exp_f32_e32 v252, v16
	v_or_b32_e32 v16, 3, v15
	v_cvt_f32_i32_e32 v16, v16
	v_mov_b64_e32 v[64:65], v[48:49]
	v_mov_b64_e32 v[60:61], v[48:49]
	v_mov_b64_e32 v[56:57], v[48:49]
	v_sub_f32_e32 v16, v16, v14
	v_cmp_lt_f32_e64 s[40:41], 0, v16
	v_mul_f32_e32 v16, v16, v12
	v_exp_f32_e32 v253, v16
	v_add_u32_e32 v16, 16, v15
	v_cvt_f32_i32_e32 v16, v16
	v_mov_b64_e32 v[52:53], v[48:49]
	s_mov_b32 s73, 0
	v_sub_f32_e32 v16, v16, v14
	v_cmp_lt_f32_e64 s[42:43], 0, v16
	v_mul_f32_e32 v16, v16, v12
	v_exp_f32_e32 v202, v16
	v_add_u32_e32 v16, 17, v15
	v_cvt_f32_i32_e32 v16, v16
	v_sub_f32_e32 v16, v16, v14
	v_cmp_lt_f32_e64 s[44:45], 0, v16
	v_mul_f32_e32 v16, v16, v12
	v_exp_f32_e32 v182, v16
	v_add_u32_e32 v16, 18, v15
	v_cvt_f32_i32_e32 v16, v16
	v_sub_f32_e32 v16, v16, v14
	v_cmp_lt_f32_e64 s[46:47], 0, v16
	v_mul_f32_e32 v16, v16, v12
	v_exp_f32_e32 v218, v16
	v_add_u32_e32 v16, 19, v15
	v_cvt_f32_i32_e32 v16, v16
	v_sub_f32_e32 v16, v16, v14
	v_cmp_lt_f32_e64 s[48:49], 0, v16
	v_mul_f32_e32 v16, v16, v12
	v_exp_f32_e32 v219, v16
	v_add_u32_e32 v16, 32, v15
	v_cvt_f32_i32_e32 v16, v16
	v_sub_f32_e32 v16, v16, v14
	v_cmp_lt_f32_e64 s[50:51], 0, v16
	v_mul_f32_e32 v16, v16, v12
	v_exp_f32_e32 v222, v16
	v_add_u32_e32 v16, 33, v15
	v_cvt_f32_i32_e32 v16, v16
	v_sub_f32_e32 v16, v16, v14
	v_cmp_lt_f32_e64 s[52:53], 0, v16
	v_mul_f32_e32 v16, v16, v12
	v_exp_f32_e32 v223, v16
	v_add_u32_e32 v16, 34, v15
	v_cvt_f32_i32_e32 v16, v16
	v_sub_f32_e32 v16, v16, v14
	v_cmp_lt_f32_e64 s[54:55], 0, v16
	v_mul_f32_e32 v16, v16, v12
	v_exp_f32_e32 v225, v16
	v_add_u32_e32 v16, 35, v15
	v_cvt_f32_i32_e32 v16, v16
	v_sub_f32_e32 v16, v16, v14
	v_cmp_lt_f32_e64 s[56:57], 0, v16
	v_mul_f32_e32 v16, v16, v12
	v_exp_f32_e32 v227, v16
	v_add_u32_e32 v16, 48, v15
	v_cvt_f32_i32_e32 v16, v16
	v_sub_f32_e32 v16, v16, v14
	v_cmp_lt_f32_e64 s[58:59], 0, v16
	v_mul_f32_e32 v16, v16, v12
	v_exp_f32_e32 v228, v16
	v_add_u32_e32 v16, 49, v15
	v_cvt_f32_i32_e32 v16, v16
	v_sub_f32_e32 v16, v16, v14
	v_cmp_lt_f32_e64 s[60:61], 0, v16
	v_mul_f32_e32 v16, v16, v12
	v_exp_f32_e32 v229, v16
	v_add_u32_e32 v16, 50, v15
	v_add_u32_e32 v15, 51, v15
	v_cvt_f32_i32_e32 v16, v16
	v_cvt_f32_i32_e32 v15, v15
	v_sub_f32_e32 v16, v16, v14
	v_sub_f32_e32 v14, v15, v14
	v_cmp_lt_f32_e64 s[62:63], 0, v16
	v_mul_f32_e32 v16, v16, v12
	v_mul_f32_e32 v12, v14, v12
	v_exp_f32_e32 v230, v16
	v_exp_f32_e32 v231, v12
	v_cmp_lt_f32_e64 s[64:65], 0, v14
	v_mov_b64_e32 v[16:17], v[48:49]
	v_mov_b64_e32 v[12:13], v[48:49]
	v_mov_b64_e32 v[18:19], v[50:51]
	v_mov_b64_e32 v[14:15], v[50:51]
	s_waitcnt vmcnt(3) lgkmcnt(0)
	s_barrier
	s_mov_b32 s98, 0
	s_and_b32 s72, s98, 3
	s_lshl_b32 s72, s72, 15
	s_add_i32 s73, s98, 3
	s_and_b32 s73, s73, 3
	s_lshl_b32 s73, s73, 15
	s_add_i32 s74, s98, 2
	s_and_b32 s74, s74, 3
	s_lshl_b32 s74, s74, 15
	s_add_i32 s74, s74, s90
	v_add_u32_e32 v212, s72, v201
	v_add_u32_e32 v213, v212, v204
	v_add_u32_e32 v214, v212, v205
	ds_read_b128 v[84:87], v213
	ds_read_b128 v[88:91], v213 offset:2048
	ds_read_b128 v[92:95], v214
	ds_read_b128 v[96:99], v214 offset:2048
	ds_read_b128 v[100:103], v213 offset:4096
	ds_read_b128 v[104:107], v213 offset:6144
	ds_read_b128 v[108:111], v214 offset:4096
	ds_read_b128 v[112:115], v214 offset:6144
	s_cmp_ge_u32 s98, s70
	s_cbranch_scc1 .Lrx_ndf
	s_mov_b32 m0, s74
	s_add_u32 s78, s2, 0x70000
	s_addc_u32 s79, s3, 0
	global_load_lds_dwordx4 v180, s[84:85]
	s_add_i32 m0, s74, 0x4000
	s_add_u32 s84, s84, 0xe0000
	s_addc_u32 s85, s85, 0
	global_load_lds_dwordx4 v184, s[2:3]
	s_add_i32 m0, s74, 0x6000
	s_add_u32 s2, s2, 0xe0000
	s_addc_u32 s3, s3, 0
	global_load_lds_dwordx4 v184, s[78:79]

; __device__ __forceinline__ void ret_pair(LAS unsigned char* lds, const bf16_t* Z, bf16_t* MIX, int b, int h, int tA, int tB, const float* gain, int wid) {
;     ...
;     int bcur = 0;
;     for (int kt = 0; kt < nkt; ++kt) {
;         const int bnx = (bcur == 2) ? 0 : bcur + 1, bn2 = (bnx == 2) ? 0 : bnx + 1;
;         const bool more2 = (kt + 2 < nkt);
;         if (more2) RP_DMA(kt + 2, bn2);
;         if (kt <= cqA) {
;             if (kt <= cqB) RP_BODY(true); else RP_BODY(false);
.Lrx_loop:
	s_and_b32 s72, s98, 3
	s_lshl_b32 s72, s72, 15
	s_add_i32 s73, s98, 3
	s_and_b32 s73, s73, 3
	s_lshl_b32 s73, s73, 15
	s_add_i32 s74, s98, 2
	s_and_b32 s74, s74, 3
	s_lshl_b32 s74, s74, 15
	s_add_i32 s74, s74, s90
	s_cmp_gt_u32 s98, s83
	s_cbranch_scc1 .Lrx_pvo
	s_cmp_le_u32 s98, s91
	s_cbranch_scc1 .Lrx_sab
	s_add_i32 s75, s98, -1
	s_cmp_le_u32 s75, s91
	s_cbranch_scc1 .Lrx_sapab
	s_waitcnt lgkmcnt(0)
	v_add_u32_e32 v212, s72, v201
	v_add_u32_e32 v213, v212, v204
	v_add_u32_e32 v214, v212, v205
	ds_read_b128 v[84:87], v213
	ds_read_b128 v[88:91], v213 offset:2048
	ds_read_b128 v[92:95], v214
	ds_read_b128 v[96:99], v214 offset:2048
	ds_read_b128 v[100:103], v213 offset:4096
	ds_read_b128 v[104:107], v213 offset:6144
	ds_read_b128 v[108:111], v214 offset:4096
	ds_read_b128 v[112:115], v214 offset:6144
	v_add_u32_e32 v215, s73, v188
	v_add_u32_e32 v248, v215, v221
	v_add_u32_e32 v249, v215, v220
	v_add_u32_e32 v250, v215, v217
	v_add_u32_e32 v251, v215, v216
	v_mfma_f32_16x16x32_bf16 v[80:83], v[116:119], v[232:235], v[80:83]
	v_mfma_f32_16x16x32_bf16 v[76:79], v[124:127], v[232:235], v[76:79]
	v_mfma_f32_16x16x32_bf16 v[80:83], v[120:123], v[236:239], v[80:83]
	v_mfma_f32_16x16x32_bf16 v[76:79], v[128:131], v[236:239], v[76:79]
	ds_read_b64_tr_b16 v[116:117], v248
	ds_read_b64_tr_b16 v[118:119], v248 offset:4096
	ds_read_b64_tr_b16 v[120:121], v248 offset:8192
	ds_read_b64_tr_b16 v[122:123], v248 offset:12288
	ds_read_b64_tr_b16 v[124:125], v249
	ds_read_b64_tr_b16 v[126:127], v249 offset:4096
	ds_read_b64_tr_b16 v[128:129], v249 offset:8192
	ds_read_b64_tr_b16 v[130:131], v249 offset:12288
	v_mfma_f32_16x16x32_bf16 v[72:75], v[132:135], v[232:235], v[72:75]
	v_mfma_f32_16x16x32_bf16 v[68:71], v[140:143], v[232:235], v[68:71]
	v_mfma_f32_16x16x32_bf16 v[72:75], v[136:139], v[236:239], v[72:75]
	v_mfma_f32_16x16x32_bf16 v[68:71], v[144:147], v[236:239], v[68:71]
	ds_read_b64_tr_b16 v[132:133], v250
	ds_read_b64_tr_b16 v[134:135], v250 offset:4096
	ds_read_b64_tr_b16 v[136:137], v250 offset:8192
	ds_read_b64_tr_b16 v[138:139], v250 offset:12288
	ds_read_b64_tr_b16 v[140:141], v251
	ds_read_b64_tr_b16 v[142:143], v251 offset:4096
	ds_read_b64_tr_b16 v[144:145], v251 offset:8192
	ds_read_b64_tr_b16 v[146:147], v251 offset:12288
	s_cmp_ge_u32 s98, s70
	s_cbranch_scc1 .Lrx_ndaa
	s_mov_b32 m0, s74
	s_add_u32 s78, s2, 0x70000
	s_addc_u32 s79, s3, 0
	global_load_lds_dwordx4 v180, s[84:85]
	s_add_i32 m0, s74, 0x4000
	s_add_u32 s84, s84, 0xe0000
	s_addc_u32 s85, s85, 0
	global_load_lds_dwordx4 v184, s[2:3]
	s_add_i32 m0, s74, 0x6000
	s_add_u32 s2, s2, 0xe0000
	s_addc_u32 s3, s3, 0
	global_load_lds_dwordx4 v184, s[78:79]

.Lrx_sapab:
	s_waitcnt lgkmcnt(0)
	v_add_u32_e32 v212, s72, v201
	v_add_u32_e32 v213, v212, v204
	v_add_u32_e32 v214, v212, v205
	ds_read_b128 v[84:87], v213
	ds_read_b128 v[88:91], v213 offset:2048
	ds_read_b128 v[92:95], v214
	ds_read_b128 v[96:99], v214 offset:2048
	ds_read_b128 v[100:103], v213 offset:4096
	ds_read_b128 v[104:107], v213 offset:6144
	ds_read_b128 v[108:111], v214 offset:4096
	ds_read_b128 v[112:115], v214 offset:6144
	v_add_u32_e32 v215, s73, v188
	v_add_u32_e32 v248, v215, v221
	v_add_u32_e32 v249, v215, v220
	v_add_u32_e32 v250, v215, v217
	v_add_u32_e32 v251, v215, v216
	v_mfma_f32_16x16x32_bf16 v[80:83], v[116:119], v[232:235], v[80:83]
	v_mfma_f32_16x16x32_bf16 v[76:79], v[124:127], v[232:235], v[76:79]
	v_mfma_f32_16x16x32_bf16 v[48:51], v[116:119], v[240:243], v[48:51]
	v_mfma_f32_16x16x32_bf16 v[44:47], v[124:127], v[240:243], v[44:47]
	v_mfma_f32_16x16x32_bf16 v[80:83], v[120:123], v[236:239], v[80:83]
	v_mfma_f32_16x16x32_bf16 v[76:79], v[128:131], v[236:239], v[76:79]
	v_mfma_f32_16x16x32_bf16 v[48:51], v[120:123], v[244:247], v[48:51]
	v_mfma_f32_16x16x32_bf16 v[44:47], v[128:131], v[244:247], v[44:47]
	ds_read_b64_tr_b16 v[116:117], v248
	ds_read_b64_tr_b16 v[118:119], v248 offset:4096
	ds_read_b64_tr_b16 v[120:121], v248 offset:8192
	ds_read_b64_tr_b16 v[122:123], v248 offset:12288
	ds_read_b64_tr_b16 v[124:125], v249
	ds_read_b64_tr_b16 v[126:127], v249 offset:4096
	ds_read_b64_tr_b16 v[128:129], v249 offset:8192
	ds_read_b64_tr_b16 v[130:131], v249 offset:12288
	v_mfma_f32_16x16x32_bf16 v[72:75], v[132:135], v[232:235], v[72:75]
	v_mfma_f32_16x16x32_bf16 v[68:71], v[140:143], v[232:235], v[68:71]
	v_mfma_f32_16x16x32_bf16 v[40:43], v[132:135], v[240:243], v[40:43]
	v_mfma_f32_16x16x32_bf16 v[36:39], v[140:143], v[240:243], v[36:39]
	v_mfma_f32_16x16x32_bf16 v[72:75], v[136:139], v[236:239], v[72:75]
	v_mfma_f32_16x16x32_bf16 v[68:71], v[144:147], v[236:239], v[68:71]
	v_mfma_f32_16x16x32_bf16 v[40:43], v[136:139], v[244:247], v[40:43]
	v_mfma_f32_16x16x32_bf16 v[36:39], v[144:147], v[244:247], v[36:39]
	ds_read_b64_tr_b16 v[132:133], v250
	ds_read_b64_tr_b16 v[134:135], v250 offset:4096
	ds_read_b64_tr_b16 v[136:137], v250 offset:8192
	ds_read_b64_tr_b16 v[138:139], v250 offset:12288
	ds_read_b64_tr_b16 v[140:141], v251
	ds_read_b64_tr_b16 v[142:143], v251 offset:4096
	ds_read_b64_tr_b16 v[144:145], v251 offset:8192
	ds_read_b64_tr_b16 v[146:147], v251 offset:12288
	s_cmp_ge_u32 s98, s70
	s_cbranch_scc1 .Lrx_ndab
	s_mov_b32 m0, s74
	s_add_u32 s78, s2, 0x70000
	s_addc_u32 s79, s3, 0
	global_load_lds_dwordx4 v180, s[84:85]
	s_add_i32 m0, s74, 0x4000
	s_add_u32 s84, s84, 0xe0000
	s_addc_u32 s85, s85, 0
	global_load_lds_dwordx4 v184, s[2:3]
	s_add_i32 m0, s74, 0x6000
	s_add_u32 s2, s2, 0xe0000
	s_addc_u32 s3, s3, 0
	global_load_lds_dwordx4 v184, s[78:79]
